# one static s_setprio 1 for waves 4-7 at kernel entry (no other setprio in the kernel)
# baseline (speedup 1.0000x reference)
_Z4mega6Params:
	v_readfirstlane_b32 s4, v0
	s_nop 3
	s_bfe_u32 s4, s4, 0x40006
	s_cmp_ge_u32 s4, 4
	s_cbranch_scc0 .Lprio_done
	s_setprio 1
.Lprio_done:
	s_load_dwordx2 s[88:89], s[0:1], 0x80
	s_add_u32 s4, s0, 0x80
	s_addc_u32 s5, s1, 0
	s_mov_b32 s33, s2
	v_mov_b32_e32 v1, 0
	s_waitcnt lgkmcnt(0)
	s_cmp_lt_u32 s2, s88
	s_cselect_b32 s2, 12, 18
	s_add_u32 s2, s4, s2
	s_addc_u32 s3, s5, 0
	global_load_ushort v2, v1, s[2:3]
	s_load_dword s10, s[0:1], 0x88
	s_load_dwordx16 s[56:71], s[0:1], 0x40
	v_and_b32_e32 v213, 0x3ff, v0
	v_cmp_gt_u32_e32 vcc, 4, v213
	s_waitcnt vmcnt(0)
	v_readfirstlane_b32 s12, v2
	s_and_saveexec_b64 s[2:3], vcc
	v_lshl_add_u32 v2, v213, 2, 0
	v_add_u32_e32 v2, 0x20d00, v2
	ds_write_b32 v2, v1
	s_or_b64 exec, exec, s[2:3]
	s_waitcnt lgkmcnt(0)
	s_barrier
	s_add_u32 s2, s70, 0x15169400
	s_getreg_b32 s6, hwreg(HW_REG_XCC_ID, 0, 4)
	s_addc_u32 s3, s71, 0
	s_and_b32 s11, s6, 15
	v_cmp_eq_u32_e64 s[16:17], 0, v213
	s_and_saveexec_b64 s[6:7], s[16:17]
	s_cbranch_execz .LBB0_5
	s_mov_b64 s[8:9], exec
	v_mbcnt_lo_u32_b32 v1, s8, 0
	v_mbcnt_hi_u32_b32 v1, s9, v1
	v_cmp_eq_u32_e32 vcc, 0, v1
	s_and_b64 s[14:15], exec, vcc
	s_mov_b64 exec, s[14:15]
	s_cbranch_execz .LBB0_5
	s_lshl_b32 s13, s11, 8
	s_bcnt1_i32_b64 s8, s[8:9]
	v_mov_b32_e32 v1, s13
	v_mov_b32_e32 v2, s8
	global_atomic_add v1, v2, s[2:3] offset:1024
